# baseline (speedup 1.0000x reference)
.Lh1a_resc_ret:
	s_add_i32 s21, s23, 2
	s_min_i32 s12, s21, 0xff
	s_mul_i32 s0, s12, 0xc0000
	s_add_u32 s0, s86, s0
	s_addc_u32 s1, s87, 0
	s_and_b32 s12, s12, 3
	s_lshl_b32 s13, s12, 13
	s_lshl_b32 s12, s12, 14
	s_add_i32 s12, s18, s12
	s_mov_b32 s82, s80
	s_mov_b32 s83, s80
	s_mov_b32 s81, s80
	v_mov_b64_e32 v[154:155], s[82:83]
	v_mov_b64_e32 v[152:153], s[80:81]
	ds_read_b128 v[240:243], v86 offset:4608
	ds_read_b128 v[244:247], v87 offset:4608
	v_mfma_f32_16x16x32_bf16 v[68:71], v[120:123], v[152:155], v[68:71]
	v_mfma_f32_16x16x32_bf16 v[56:59], v[124:127], v[152:155], v[56:59]
	v_mfma_f32_16x16x32_bf16 v[68:71], v[112:115], v[152:155], v[68:71]
	v_mfma_f32_16x16x32_bf16 v[56:59], v[116:119], v[152:155], v[56:59]
	s_waitcnt lgkmcnt(6)
	ds_read_b64_tr_b16 v[128:129], v212
	ds_read_b64_tr_b16 v[130:131], v212 offset:4096
	ds_read_b64_tr_b16 v[132:133], v212 offset:8192
	ds_read_b64_tr_b16 v[134:135], v212 offset:12288
	v_mfma_f32_16x16x32_bf16 v[84:87], v[160:163], v[176:179], v[72:75]
	v_mfma_f32_16x16x32_bf16 v[80:83], v[160:163], v[180:183], v[76:79]
	v_mfma_f32_16x16x32_bf16 v[84:87], v[164:167], v[184:187], v[84:87]
	s_add_i32 m0, s17, s13
	v_mfma_f32_16x16x32_bf16 v[80:83], v[164:167], v[188:191], v[80:83]
	global_load_lds_dwordx4 v232, s[0:1]
	s_waitcnt lgkmcnt(8)
	ds_read_b64_tr_b16 v[136:137], v213
	ds_read_b64_tr_b16 v[138:139], v213 offset:4096
	ds_read_b64_tr_b16 v[148:149], v213 offset:8192
	ds_read_b64_tr_b16 v[150:151], v213 offset:12288
	v_mfma_f32_16x16x32_bf16 v[96:99], v[168:171], v[176:179], v[72:75]
	v_mfma_f32_16x16x32_bf16 v[88:91], v[168:171], v[180:183], v[76:79]
	v_mfma_f32_16x16x32_bf16 v[96:99], v[172:175], v[184:187], v[96:99]
	s_mov_b32 m0, s12
	v_mfma_f32_16x16x32_bf16 v[88:91], v[172:175], v[188:191], v[88:91]
	global_load_lds_dwordx4 v233, s[0:1]
	s_waitcnt lgkmcnt(10)
	ds_read_b64_tr_b16 v[152:153], v212 offset:1024
	ds_read_b64_tr_b16 v[154:155], v212 offset:5120
	ds_read_b64_tr_b16 v[156:157], v212 offset:9216
	ds_read_b64_tr_b16 v[158:159], v212 offset:13312
	v_mfma_f32_16x16x32_bf16 v[100:103], v[140:143], v[176:179], v[72:75]
	v_mfma_f32_16x16x32_bf16 v[92:95], v[140:143], v[180:183], v[76:79]
	v_mfma_f32_16x16x32_bf16 v[100:103], v[144:147], v[184:187], v[100:103]
	s_add_i32 m0, s12, 0x2000
	v_mfma_f32_16x16x32_bf16 v[92:95], v[144:147], v[188:191], v[92:95]
	global_load_lds_dwordx4 v234, s[0:1]
	s_waitcnt lgkmcnt(12)
	v_mfma_f32_16x16x32_bf16 v[108:111], v[240:243], v[176:179], v[72:75]
	v_mfma_f32_16x16x32_bf16 v[104:107], v[240:243], v[180:183], v[76:79]
	v_mfma_f32_16x16x32_bf16 v[108:111], v[244:247], v[184:187], v[108:111]
	v_mfma_f32_16x16x32_bf16 v[104:107], v[244:247], v[188:191], v[104:107]
	s_cmp_le_i32 s23, s75
	s_cbranch_scc0 .LBB0_379

.Lh2a_resc_ret:
	s_min_i32 s0, s23, 0xfc
	s_add_i32 s6, s0, 3
	s_mul_i32 s0, s6, 0xc0000
	s_add_u32 s0, s86, s0
	s_addc_u32 s1, s87, 0
	s_and_b32 s6, s6, 3
	s_lshl_b32 s7, s6, 13
	s_lshl_b32 s6, s6, 14
	s_add_i32 s6, s18, s6
	s_mov_b32 s82, s80
	s_mov_b32 s83, s80
	s_mov_b32 s81, s80
	v_mov_b64_e32 v[186:187], s[82:83]
	v_mov_b64_e32 v[184:185], s[80:81]
	ds_read_b128 v[160:163], v86 offset:4608
	ds_read_b128 v[164:167], v87 offset:4608
	v_mfma_f32_16x16x32_bf16 v[68:71], v[120:123], v[184:187], v[68:71]
	v_mfma_f32_16x16x32_bf16 v[56:59], v[124:127], v[184:187], v[56:59]
	v_mfma_f32_16x16x32_bf16 v[68:71], v[112:115], v[184:187], v[68:71]
	v_mfma_f32_16x16x32_bf16 v[56:59], v[116:119], v[184:187], v[56:59]
	s_waitcnt lgkmcnt(6)
	ds_read_b64_tr_b16 v[168:169], v214
	ds_read_b64_tr_b16 v[170:171], v214 offset:4096
	ds_read_b64_tr_b16 v[172:173], v214 offset:8192
	ds_read_b64_tr_b16 v[174:175], v214 offset:12288
	v_mfma_f32_16x16x32_bf16 v[84:87], v[128:131], v[240:243], v[72:75]
	v_mfma_f32_16x16x32_bf16 v[80:83], v[128:131], v[244:247], v[76:79]
	v_mfma_f32_16x16x32_bf16 v[84:87], v[132:135], v[152:155], v[84:87]
	s_add_i32 m0, s17, s7
	v_mfma_f32_16x16x32_bf16 v[80:83], v[132:135], v[156:159], v[80:83]
	global_load_lds_dwordx4 v232, s[0:1]
	s_waitcnt lgkmcnt(8)
	ds_read_b64_tr_b16 v[176:177], v215
	ds_read_b64_tr_b16 v[178:179], v215 offset:4096
	ds_read_b64_tr_b16 v[180:181], v215 offset:8192
	ds_read_b64_tr_b16 v[182:183], v215 offset:12288
	v_mfma_f32_16x16x32_bf16 v[96:99], v[136:139], v[240:243], v[72:75]
	v_mfma_f32_16x16x32_bf16 v[88:91], v[136:139], v[244:247], v[76:79]
	v_mfma_f32_16x16x32_bf16 v[96:99], v[148:151], v[152:155], v[96:99]
	s_mov_b32 m0, s6
	v_mfma_f32_16x16x32_bf16 v[88:91], v[148:151], v[156:159], v[88:91]
	global_load_lds_dwordx4 v233, s[0:1]
	s_waitcnt lgkmcnt(10)
	ds_read_b64_tr_b16 v[184:185], v214 offset:1024
	ds_read_b64_tr_b16 v[186:187], v214 offset:5120
	ds_read_b64_tr_b16 v[188:189], v214 offset:9216
	ds_read_b64_tr_b16 v[190:191], v214 offset:13312
	v_mfma_f32_16x16x32_bf16 v[100:103], v[140:143], v[240:243], v[72:75]
	v_mfma_f32_16x16x32_bf16 v[92:95], v[140:143], v[244:247], v[76:79]
	v_mfma_f32_16x16x32_bf16 v[100:103], v[144:147], v[152:155], v[100:103]
	s_add_i32 m0, s6, 0x2000
	v_mfma_f32_16x16x32_bf16 v[92:95], v[144:147], v[156:159], v[92:95]
	global_load_lds_dwordx4 v234, s[0:1]
	s_waitcnt lgkmcnt(12)
	v_mfma_f32_16x16x32_bf16 v[108:111], v[160:163], v[240:243], v[72:75]
	v_mfma_f32_16x16x32_bf16 v[104:107], v[160:163], v[244:247], v[76:79]
	v_mfma_f32_16x16x32_bf16 v[108:111], v[164:167], v[152:155], v[108:111]
	v_mfma_f32_16x16x32_bf16 v[104:107], v[164:167], v[156:159], v[104:107]
	s_cmp_lt_i32 s23, s75
	s_cbranch_scc0 .LBB0_384

.Lh1b_resc_ret:
	s_add_i32 s17, s19, 2
	s_min_i32 s10, s17, 0xff
	s_mul_i32 s0, s10, 0xc0000
	s_add_u32 s0, s86, s0
	s_addc_u32 s1, s87, 0
	s_and_b32 s10, s10, 3
	s_lshl_b32 s11, s10, 13
	s_lshl_b32 s10, s10, 14
	s_add_i32 s10, s13, s10
	s_mov_b32 s82, s80
	s_mov_b32 s83, s80
	s_mov_b32 s81, s80
	v_mov_b64_e32 v[154:155], s[82:83]
	v_mov_b64_e32 v[152:153], s[80:81]
	ds_read_b128 v[240:243], v86 offset:4608
	ds_read_b128 v[244:247], v87 offset:4608
	v_mfma_f32_16x16x32_bf16 v[68:71], v[120:123], v[152:155], v[68:71]
	v_mfma_f32_16x16x32_bf16 v[56:59], v[124:127], v[152:155], v[56:59]
	v_mfma_f32_16x16x32_bf16 v[68:71], v[112:115], v[152:155], v[68:71]
	v_mfma_f32_16x16x32_bf16 v[56:59], v[116:119], v[152:155], v[56:59]
	s_waitcnt lgkmcnt(6)
	ds_read_b64_tr_b16 v[128:129], v212
	ds_read_b64_tr_b16 v[130:131], v212 offset:4096
	ds_read_b64_tr_b16 v[132:133], v212 offset:8192
	ds_read_b64_tr_b16 v[134:135], v212 offset:12288
	v_mfma_f32_16x16x32_bf16 v[84:87], v[160:163], v[176:179], v[72:75]
	v_mfma_f32_16x16x32_bf16 v[80:83], v[160:163], v[180:183], v[76:79]
	v_mfma_f32_16x16x32_bf16 v[84:87], v[164:167], v[184:187], v[84:87]
	s_add_i32 m0, s12, s11
	v_mfma_f32_16x16x32_bf16 v[80:83], v[164:167], v[188:191], v[80:83]
	global_load_lds_dwordx4 v232, s[0:1]
	s_waitcnt lgkmcnt(8)
	ds_read_b64_tr_b16 v[136:137], v213
	ds_read_b64_tr_b16 v[138:139], v213 offset:4096
	ds_read_b64_tr_b16 v[148:149], v213 offset:8192
	ds_read_b64_tr_b16 v[150:151], v213 offset:12288
	v_mfma_f32_16x16x32_bf16 v[96:99], v[168:171], v[176:179], v[72:75]
	v_mfma_f32_16x16x32_bf16 v[88:91], v[168:171], v[180:183], v[76:79]
	v_mfma_f32_16x16x32_bf16 v[96:99], v[172:175], v[184:187], v[96:99]
	s_mov_b32 m0, s10
	v_mfma_f32_16x16x32_bf16 v[88:91], v[172:175], v[188:191], v[88:91]
	global_load_lds_dwordx4 v233, s[0:1]
	s_waitcnt lgkmcnt(10)
	ds_read_b64_tr_b16 v[152:153], v212 offset:1024
	ds_read_b64_tr_b16 v[154:155], v212 offset:5120
	ds_read_b64_tr_b16 v[156:157], v212 offset:9216
	ds_read_b64_tr_b16 v[158:159], v212 offset:13312
	v_mfma_f32_16x16x32_bf16 v[100:103], v[140:143], v[176:179], v[72:75]
	v_mfma_f32_16x16x32_bf16 v[92:95], v[140:143], v[180:183], v[76:79]
	v_mfma_f32_16x16x32_bf16 v[100:103], v[144:147], v[184:187], v[100:103]
	s_add_i32 m0, s10, 0x2000
	v_mfma_f32_16x16x32_bf16 v[92:95], v[144:147], v[188:191], v[92:95]
	global_load_lds_dwordx4 v234, s[0:1]
	s_waitcnt lgkmcnt(12)
	v_mfma_f32_16x16x32_bf16 v[108:111], v[240:243], v[176:179], v[72:75]
	v_mfma_f32_16x16x32_bf16 v[104:107], v[240:243], v[180:183], v[76:79]
	v_mfma_f32_16x16x32_bf16 v[108:111], v[244:247], v[184:187], v[108:111]
	v_mfma_f32_16x16x32_bf16 v[104:107], v[244:247], v[188:191], v[104:107]
	s_cmp_le_i32 s19, s75
	s_cbranch_scc0 .LBB0_406

.Lh2b_resc_ret:
	s_min_i32 s0, s19, 0xfc
	s_add_i32 s6, s0, 3
	s_mul_i32 s0, s6, 0xc0000
	s_add_u32 s0, s86, s0
	s_addc_u32 s1, s87, 0
	s_and_b32 s6, s6, 3
	s_lshl_b32 s7, s6, 13
	s_lshl_b32 s6, s6, 14
	s_add_i32 s6, s13, s6
	s_mov_b32 s82, s80
	s_mov_b32 s83, s80
	s_mov_b32 s81, s80
	v_mov_b64_e32 v[186:187], s[82:83]
	v_mov_b64_e32 v[184:185], s[80:81]
	ds_read_b128 v[160:163], v86 offset:4608
	ds_read_b128 v[164:167], v87 offset:4608
	v_mfma_f32_16x16x32_bf16 v[68:71], v[120:123], v[184:187], v[68:71]
	v_mfma_f32_16x16x32_bf16 v[56:59], v[124:127], v[184:187], v[56:59]
	v_mfma_f32_16x16x32_bf16 v[68:71], v[112:115], v[184:187], v[68:71]
	v_mfma_f32_16x16x32_bf16 v[56:59], v[116:119], v[184:187], v[56:59]
	s_waitcnt lgkmcnt(6)
	ds_read_b64_tr_b16 v[168:169], v214
	ds_read_b64_tr_b16 v[170:171], v214 offset:4096
	ds_read_b64_tr_b16 v[172:173], v214 offset:8192
	ds_read_b64_tr_b16 v[174:175], v214 offset:12288
	v_mfma_f32_16x16x32_bf16 v[84:87], v[128:131], v[240:243], v[72:75]
	v_mfma_f32_16x16x32_bf16 v[80:83], v[128:131], v[244:247], v[76:79]
	v_mfma_f32_16x16x32_bf16 v[84:87], v[132:135], v[152:155], v[84:87]
	s_add_i32 m0, s12, s7
	v_mfma_f32_16x16x32_bf16 v[80:83], v[132:135], v[156:159], v[80:83]
	global_load_lds_dwordx4 v232, s[0:1]
	s_waitcnt lgkmcnt(8)
	ds_read_b64_tr_b16 v[176:177], v215
	ds_read_b64_tr_b16 v[178:179], v215 offset:4096
	ds_read_b64_tr_b16 v[180:181], v215 offset:8192
	ds_read_b64_tr_b16 v[182:183], v215 offset:12288
	v_mfma_f32_16x16x32_bf16 v[96:99], v[136:139], v[240:243], v[72:75]
	v_mfma_f32_16x16x32_bf16 v[88:91], v[136:139], v[244:247], v[76:79]
	v_mfma_f32_16x16x32_bf16 v[96:99], v[148:151], v[152:155], v[96:99]
	s_mov_b32 m0, s6
	v_mfma_f32_16x16x32_bf16 v[88:91], v[148:151], v[156:159], v[88:91]
	global_load_lds_dwordx4 v233, s[0:1]
	s_waitcnt lgkmcnt(10)
	ds_read_b64_tr_b16 v[184:185], v214 offset:1024
	ds_read_b64_tr_b16 v[186:187], v214 offset:5120
	ds_read_b64_tr_b16 v[188:189], v214 offset:9216
	ds_read_b64_tr_b16 v[190:191], v214 offset:13312
	v_mfma_f32_16x16x32_bf16 v[100:103], v[140:143], v[240:243], v[72:75]
	v_mfma_f32_16x16x32_bf16 v[92:95], v[140:143], v[244:247], v[76:79]
	v_mfma_f32_16x16x32_bf16 v[100:103], v[144:147], v[152:155], v[100:103]
	s_add_i32 m0, s6, 0x2000
	v_mfma_f32_16x16x32_bf16 v[92:95], v[144:147], v[156:159], v[92:95]
	global_load_lds_dwordx4 v234, s[0:1]
	s_waitcnt lgkmcnt(12)
	v_mfma_f32_16x16x32_bf16 v[108:111], v[160:163], v[240:243], v[72:75]
	v_mfma_f32_16x16x32_bf16 v[104:107], v[160:163], v[244:247], v[76:79]
	v_mfma_f32_16x16x32_bf16 v[108:111], v[164:167], v[152:155], v[108:111]
	v_mfma_f32_16x16x32_bf16 v[104:107], v[164:167], v[156:159], v[104:107]
	s_cmp_lt_i32 s19, s75
	s_cbranch_scc0 .LBB0_411
